# GEMM main loop: 8 phases merged pairwise into 4 (32-MFMA bursts, half the barriers, LDS reads drained before the barrier)
# speedup vs baseline: 1.0152x; 1.0070x over previous
.LBB0_265:
	v_mov_b32_e32 v153, v28
	v_lshl_add_u64 v[14:15], v[130:131], 0, v[152:153]
	v_mov_b32_e32 v157, v28
	v_lshl_add_u64 v[16:17], v[130:131], 0, v[156:157]
	s_add_i32 m0, s67, 0x1a400
	v_lshl_add_u64 v[14:15], v[14:15], 0, s[52:53]
	s_waitcnt vmcnt(2)
	s_barrier
	global_load_lds_dwordx4 v[14:15], off
	v_lshl_add_u64 v[14:15], v[16:17], 0, s[52:53]
	s_add_i32 m0, s67, 0x1c400
	s_add_i32 s64, s67, 0xa400
	global_load_lds_dwordx4 v[14:15], off
	v_lshl_add_u64 v[2:3], v[2:3], 0, s[52:53]
	s_mov_b32 m0, s64
	s_add_i32 s65, s67, 0xc400
	v_lshl_add_u64 v[18:19], v[4:5], 0, v[152:153]
	global_load_lds_dwordx4 v[2:3], off
	v_lshl_add_u64 v[0:1], v[0:1], 0, s[52:53]
	s_mov_b32 m0, s65
	v_lshl_add_u64 v[4:5], v[4:5], 0, v[156:157]
	global_load_lds_dwordx4 v[0:1], off
	s_add_i32 m0, s67, 0x1e400
	v_lshl_add_u64 v[0:1], v[18:19], 0, s[52:53]
	global_load_lds_dwordx4 v[0:1], off
	v_lshl_add_u64 v[0:1], v[4:5], 0, s[52:53]
	s_add_i32 m0, s67, 0x20400
	s_ashr_i32 s0, s12, 31
	global_load_lds_dwordx4 v[0:1], off
	v_bfe_u32 v13, v6, 4, 2
	s_lshr_b32 s0, s0, 26
	v_and_b32_e32 v20, 15, v6
	s_add_i32 s0, s12, s0
	v_lshlrev_b32_e32 v21, 4, v13
	v_lshlrev_b32_e32 v6, 2, v6
	s_ashr_i32 s62, s0, 6
	v_lshl_or_b32 v29, s2, 6, v20
	v_lshl_or_b32 v20, v20, 6, v21
	s_lshl_b32 s0, s2, 13
	v_and_b32_e32 v6, 32, v6
	v_bitop3_b32 v21, v20, s0, v6 bitop3:0xde
	s_lshl_b32 s0, s3, 5
	s_and_b32 s1, s0, 0x60
	s_lshl_b32 s0, s1, 7
	s_cmp_gt_i32 s12, 63
	s_cselect_b64 s[28:29], -1, 0
	s_cmp_gt_i32 s43, 1
	v_bitop3_b32 v151, v20, s0, v6 bitop3:0xde
	s_cselect_b64 s[30:31], -1, 0
	s_add_i32 s66, s62, -2
	s_add_i32 s67, s67, 0xe400
	s_add_i32 s0, s43, -1
	s_cmp_lg_u32 s43, 2
	s_cselect_b64 s[34:35], -1, 0
	s_and_b32 s68, s0, -2
	s_or_b32 s2, s0, 1
	s_cmp_lg_u32 s0, s68
	v_add_u32_e32 v0, v12, v10
	v_writelane_b32 v244, s2, 39
	s_cselect_b64 s[2:3], -1, 0
	v_add_lshl_u32 v0, v0, v11, 1
	v_mov_b32_e32 v1, v28
	s_waitcnt vmcnt(6)
	v_writelane_b32 v244, s2, 40
	v_lshl_add_u64 v[158:159], s[20:21], 0, v[0:1]
	v_add_u32_e32 v0, v9, v7
	v_add_u32_e32 v176, 0, v21
	v_lshlrev_b32_e32 v178, 2, v13
	v_writelane_b32 v244, s3, 41
	v_add_lshl_u32 v0, v0, v8, 1
	v_add_u32_e32 v177, 0xe400, v176
	v_writelane_b32 v244, s1, 42
	v_or_b32_e32 v179, s1, v178
	s_add_i32 s70, s42, 0x1478
	s_add_i32 s0, s42, 0x1438
	v_lshl_add_u64 v[160:161], s[20:21], 0, v[0:1]
	s_mov_b32 s72, 0
	s_add_i32 s73, s67, 0x2000
	s_barrier
	v_writelane_b32 v244, s0, 43
	s_branch .LBB0_267

.LBB0_287:
	s_add_i32 s4, s2, 2
	s_add_u32 s5, s0, 0x80
	s_addc_u32 s3, s1, 0
	s_add_i32 s10, 0, 0x12400
	v_add_u32_e32 v144, s10, v151
	ds_read_b128 v[132:135], v144
	ds_read_b128 v[136:139], v144 offset:1024
	ds_read_b128 v[140:143], v144 offset:2048
	ds_read_b128 v[164:167], v144 offset:3072
	s_cmp_eq_u32 s66, s2
	s_cselect_b32 s2, s38, s5
	s_cselect_b64 vcc, -1, 0
	s_cselect_b32 s3, s39, s3
	v_cndmask_b32_e32 v145, v131, v163, vcc
	v_cndmask_b32_e32 v144, v130, v162, vcc
	s_mov_b32 m0, s67
	v_lshl_add_u64 v[248:249], s[0:1], 0, v[160:161]
	ds_read_b128 v[168:171], v176 offset:9216
	ds_read_b128 v[172:175], v176 offset:10240
	ds_read_b128 v[180:183], v176 offset:11264
	ds_read_b128 v[184:187], v176 offset:12288
	ds_read_b128 v[188:191], v176 offset:13312
	ds_read_b128 v[192:195], v176 offset:14336
	ds_read_b128 v[210:213], v176 offset:15360
	ds_read_b128 v[214:217], v176 offset:16384
	s_add_i32 s5, 0, 0x16400
	v_add_u32_e32 v209, s5, v151
	ds_read_b128 v[218:221], v209
	ds_read_b128 v[222:225], v209 offset:1024
	ds_read_b128 v[226:229], v209 offset:2048
	ds_read_b128 v[230:233], v209 offset:3072
	global_load_lds_dwordx4 v[248:249], off
	v_lshl_add_u64 v[250:251], s[0:1], 0, v[158:159]
	s_mov_b32 m0, s73
	s_nop 0
	global_load_lds_dwordx4 v[250:251], off
	s_waitcnt vmcnt(8) lgkmcnt(0)
	s_barrier
	s_setprio 1
	v_mfma_f32_16x16x32_bf16 v[114:117], v[132:135], v[168:171], v[114:117]
	v_mfma_f32_16x16x32_bf16 v[126:129], v[140:143], v[168:171], v[126:129]
	v_mfma_f32_16x16x32_bf16 v[110:113], v[132:135], v[180:183], v[110:113]
	v_mfma_f32_16x16x32_bf16 v[106:109], v[140:143], v[180:183], v[106:109]
	v_mfma_f32_16x16x32_bf16 v[94:97], v[132:135], v[188:191], v[94:97]
	v_mfma_f32_16x16x32_bf16 v[90:93], v[140:143], v[188:191], v[90:93]
	v_mfma_f32_16x16x32_bf16 v[78:81], v[132:135], v[210:213], v[78:81]
	v_mfma_f32_16x16x32_bf16 v[74:77], v[140:143], v[210:213], v[74:77]
	v_mfma_f32_16x16x32_bf16 v[114:117], v[136:139], v[172:175], v[114:117]
	v_mfma_f32_16x16x32_bf16 v[126:129], v[164:167], v[172:175], v[126:129]
	v_mfma_f32_16x16x32_bf16 v[110:113], v[136:139], v[184:187], v[110:113]
	v_mfma_f32_16x16x32_bf16 v[106:109], v[164:167], v[184:187], v[106:109]
	v_mfma_f32_16x16x32_bf16 v[94:97], v[136:139], v[192:195], v[94:97]
	v_mfma_f32_16x16x32_bf16 v[90:93], v[164:167], v[192:195], v[90:93]
	v_mfma_f32_16x16x32_bf16 v[78:81], v[136:139], v[214:217], v[78:81]
	v_mfma_f32_16x16x32_bf16 v[74:77], v[164:167], v[214:217], v[74:77]
	v_mfma_f32_16x16x32_bf16 v[122:125], v[218:221], v[168:171], v[122:125]
	v_mfma_f32_16x16x32_bf16 v[118:121], v[226:229], v[168:171], v[118:121]
	v_mfma_f32_16x16x32_bf16 v[102:105], v[218:221], v[180:183], v[102:105]
	v_mfma_f32_16x16x32_bf16 v[98:101], v[226:229], v[180:183], v[98:101]
	v_mfma_f32_16x16x32_bf16 v[86:89], v[218:221], v[188:191], v[86:89]
	v_mfma_f32_16x16x32_bf16 v[82:85], v[226:229], v[188:191], v[82:85]
	v_mfma_f32_16x16x32_bf16 v[70:73], v[218:221], v[210:213], v[70:73]
	v_mfma_f32_16x16x32_bf16 v[66:69], v[226:229], v[210:213], v[66:69]
	v_mfma_f32_16x16x32_bf16 v[122:125], v[222:225], v[172:175], v[122:125]
	v_mfma_f32_16x16x32_bf16 v[118:121], v[230:233], v[172:175], v[118:121]
	v_mfma_f32_16x16x32_bf16 v[102:105], v[222:225], v[184:187], v[102:105]
	v_mfma_f32_16x16x32_bf16 v[98:101], v[230:233], v[184:187], v[98:101]
	v_mfma_f32_16x16x32_bf16 v[86:89], v[222:225], v[192:195], v[86:89]
	v_mfma_f32_16x16x32_bf16 v[82:85], v[230:233], v[192:195], v[82:85]
	v_mfma_f32_16x16x32_bf16 v[70:73], v[222:225], v[214:217], v[70:73]
	v_mfma_f32_16x16x32_bf16 v[66:69], v[230:233], v[214:217], v[66:69]
	s_setprio 0
	s_barrier
	ds_read_b128 v[168:171], v176 offset:26624
	ds_read_b128 v[172:175], v176 offset:27648
	ds_read_b128 v[180:183], v176 offset:28672
	ds_read_b128 v[184:187], v176 offset:29696
	ds_read_b128 v[188:191], v176 offset:30720
	ds_read_b128 v[192:195], v176 offset:31744
	ds_read_b128 v[210:213], v176 offset:25600
	ds_read_b128 v[214:217], v176 offset:32768
	s_add_i32 s10, s10, s45
	v_lshl_add_u64 v[234:235], v[144:145], 0, v[152:153]
	s_mov_b32 m0, s10
	v_lshl_add_u64 v[236:237], v[144:145], 0, v[156:157]
	global_load_lds_dwordx4 v[234:235], off
	s_add_i32 m0, s10, 0x2000
	v_lshl_add_u64 v[238:239], s[2:3], 0, v[146:147]
	global_load_lds_dwordx4 v[236:237], off
	s_mov_b32 m0, s46
	v_lshl_add_u64 v[240:241], s[2:3], 0, v[154:155]
	global_load_lds_dwordx4 v[238:239], off
	s_mov_b32 m0, s47
	v_lshl_add_u64 v[248:249], v[144:145], 0, s[22:23]
	global_load_lds_dwordx4 v[240:241], off
	s_add_i32 s5, s5, s45
	v_lshl_add_u64 v[144:145], v[248:249], 0, v[152:153]
	s_mov_b32 m0, s5
	v_lshl_add_u64 v[242:243], v[248:249], 0, v[156:157]
	global_load_lds_dwordx4 v[144:145], off
	s_add_i32 m0, s5, 0x2000
	s_nop 0
	global_load_lds_dwordx4 v[242:243], off
	s_waitcnt vmcnt(8) lgkmcnt(0)
	s_barrier
	s_setprio 1
	v_mfma_f32_16x16x32_bf16 v[62:65], v[132:135], v[210:213], v[62:65]
	v_mfma_f32_16x16x32_bf16 v[58:61], v[140:143], v[210:213], v[58:61]
	v_mfma_f32_16x16x32_bf16 v[46:49], v[132:135], v[172:175], v[46:49]
	v_mfma_f32_16x16x32_bf16 v[42:45], v[140:143], v[172:175], v[42:45]
	v_mfma_f32_16x16x32_bf16 v[30:33], v[132:135], v[184:187], v[30:33]
	v_mfma_f32_16x16x32_bf16 v[24:27], v[140:143], v[184:187], v[24:27]
	v_mfma_f32_16x16x32_bf16 v[12:15], v[132:135], v[192:195], v[12:15]
	v_mfma_f32_16x16x32_bf16 v[8:11], v[140:143], v[192:195], v[8:11]
	v_mfma_f32_16x16x32_bf16 v[62:65], v[136:139], v[168:171], v[62:65]
	v_mfma_f32_16x16x32_bf16 v[58:61], v[164:167], v[168:171], v[58:61]
	v_mfma_f32_16x16x32_bf16 v[46:49], v[136:139], v[180:183], v[46:49]
	v_mfma_f32_16x16x32_bf16 v[42:45], v[164:167], v[180:183], v[42:45]
	v_mfma_f32_16x16x32_bf16 v[30:33], v[136:139], v[188:191], v[30:33]
	v_mfma_f32_16x16x32_bf16 v[24:27], v[164:167], v[188:191], v[24:27]
	v_mfma_f32_16x16x32_bf16 v[12:15], v[136:139], v[214:217], v[12:15]
	v_mfma_f32_16x16x32_bf16 v[8:11], v[164:167], v[214:217], v[8:11]
	v_mfma_f32_16x16x32_bf16 v[54:57], v[218:221], v[210:213], v[54:57]
	v_mfma_f32_16x16x32_bf16 v[50:53], v[226:229], v[210:213], v[50:53]
	v_mfma_f32_16x16x32_bf16 v[38:41], v[218:221], v[172:175], v[38:41]
	v_mfma_f32_16x16x32_bf16 v[34:37], v[226:229], v[172:175], v[34:37]
	v_mfma_f32_16x16x32_bf16 v[20:23], v[218:221], v[184:187], v[20:23]
	v_mfma_f32_16x16x32_bf16 v[16:19], v[226:229], v[184:187], v[16:19]
	v_mfma_f32_16x16x32_bf16 v[4:7], v[218:221], v[192:195], v[4:7]
	v_mfma_f32_16x16x32_bf16 v[0:3], v[226:229], v[192:195], v[0:3]
	v_mfma_f32_16x16x32_bf16 v[54:57], v[222:225], v[168:171], v[54:57]
	v_mfma_f32_16x16x32_bf16 v[50:53], v[230:233], v[168:171], v[50:53]
	v_mfma_f32_16x16x32_bf16 v[38:41], v[222:225], v[180:183], v[38:41]
	v_mfma_f32_16x16x32_bf16 v[34:37], v[230:233], v[180:183], v[34:37]
	v_mfma_f32_16x16x32_bf16 v[20:23], v[222:225], v[188:191], v[20:23]
	v_mfma_f32_16x16x32_bf16 v[16:19], v[230:233], v[188:191], v[16:19]
	v_mfma_f32_16x16x32_bf16 v[4:7], v[222:225], v[214:217], v[4:7]
	v_mfma_f32_16x16x32_bf16 v[0:3], v[230:233], v[214:217], v[0:3]
	s_setprio 0
	s_add_i32 s5, 0, 0x1a400
	v_add_u32_e32 v164, s5, v151
	s_barrier
	ds_read_b128 v[132:135], v164
	ds_read_b128 v[136:139], v164 offset:1024
	ds_read_b128 v[140:143], v164 offset:2048
	ds_read_b128 v[164:167], v164 offset:3072
	s_add_u32 s2, s2, s20
	s_addc_u32 s3, s3, s21
	s_mov_b32 m0, s48
	v_lshl_add_u64 v[248:249], s[2:3], 0, v[146:147]
	ds_read_b128 v[168:171], v176 offset:41984
	ds_read_b128 v[172:175], v176 offset:43008
	ds_read_b128 v[180:183], v176 offset:44032
	ds_read_b128 v[184:187], v176 offset:45056
	ds_read_b128 v[188:191], v176 offset:46080
	ds_read_b128 v[192:195], v176 offset:47104
	ds_read_b128 v[210:213], v176 offset:48128
	ds_read_b128 v[214:217], v176 offset:49152
	v_lshl_add_u64 v[250:251], s[2:3], 0, v[154:155]
	s_add_i32 s2, 0, 0x1e400
	v_add_u32_e32 v209, s2, v151
	ds_read_b128 v[218:221], v209
	ds_read_b128 v[222:225], v209 offset:1024
	ds_read_b128 v[226:229], v209 offset:2048
	ds_read_b128 v[230:233], v209 offset:3072
	global_load_lds_dwordx4 v[248:249], off
	s_mov_b32 m0, s49
	s_nop 0
	global_load_lds_dwordx4 v[250:251], off
	s_waitcnt vmcnt(8) lgkmcnt(0)
	s_barrier
	s_setprio 1
	v_mfma_f32_16x16x32_bf16 v[114:117], v[132:135], v[168:171], v[114:117]
	v_mfma_f32_16x16x32_bf16 v[126:129], v[140:143], v[168:171], v[126:129]
	v_mfma_f32_16x16x32_bf16 v[110:113], v[132:135], v[180:183], v[110:113]
	v_mfma_f32_16x16x32_bf16 v[106:109], v[140:143], v[180:183], v[106:109]
	v_mfma_f32_16x16x32_bf16 v[94:97], v[132:135], v[188:191], v[94:97]
	v_mfma_f32_16x16x32_bf16 v[90:93], v[140:143], v[188:191], v[90:93]
	v_mfma_f32_16x16x32_bf16 v[78:81], v[132:135], v[210:213], v[78:81]
	v_mfma_f32_16x16x32_bf16 v[74:77], v[140:143], v[210:213], v[74:77]
	v_mfma_f32_16x16x32_bf16 v[114:117], v[136:139], v[172:175], v[114:117]
	v_mfma_f32_16x16x32_bf16 v[126:129], v[164:167], v[172:175], v[126:129]
	v_mfma_f32_16x16x32_bf16 v[110:113], v[136:139], v[184:187], v[110:113]
	v_mfma_f32_16x16x32_bf16 v[106:109], v[164:167], v[184:187], v[106:109]
	v_mfma_f32_16x16x32_bf16 v[94:97], v[136:139], v[192:195], v[94:97]
	v_mfma_f32_16x16x32_bf16 v[90:93], v[164:167], v[192:195], v[90:93]
	v_mfma_f32_16x16x32_bf16 v[78:81], v[136:139], v[214:217], v[78:81]
	v_mfma_f32_16x16x32_bf16 v[74:77], v[164:167], v[214:217], v[74:77]
	v_mfma_f32_16x16x32_bf16 v[122:125], v[218:221], v[168:171], v[122:125]
	v_mfma_f32_16x16x32_bf16 v[118:121], v[226:229], v[168:171], v[118:121]
	v_mfma_f32_16x16x32_bf16 v[102:105], v[218:221], v[180:183], v[102:105]
	v_mfma_f32_16x16x32_bf16 v[98:101], v[226:229], v[180:183], v[98:101]
	v_mfma_f32_16x16x32_bf16 v[86:89], v[218:221], v[188:191], v[86:89]
	v_mfma_f32_16x16x32_bf16 v[82:85], v[226:229], v[188:191], v[82:85]
	v_mfma_f32_16x16x32_bf16 v[70:73], v[218:221], v[210:213], v[70:73]
	v_mfma_f32_16x16x32_bf16 v[66:69], v[226:229], v[210:213], v[66:69]
	v_mfma_f32_16x16x32_bf16 v[122:125], v[222:225], v[172:175], v[122:125]
	v_mfma_f32_16x16x32_bf16 v[118:121], v[230:233], v[172:175], v[118:121]
	v_mfma_f32_16x16x32_bf16 v[102:105], v[222:225], v[184:187], v[102:105]
	v_mfma_f32_16x16x32_bf16 v[98:101], v[230:233], v[184:187], v[98:101]
	v_mfma_f32_16x16x32_bf16 v[86:89], v[222:225], v[192:195], v[86:89]
	v_mfma_f32_16x16x32_bf16 v[82:85], v[230:233], v[192:195], v[82:85]
	v_mfma_f32_16x16x32_bf16 v[70:73], v[222:225], v[214:217], v[70:73]
	v_mfma_f32_16x16x32_bf16 v[66:69], v[230:233], v[214:217], v[66:69]
	s_setprio 0
	s_barrier
	ds_read_b128 v[168:171], v176 offset:58368
	ds_read_b128 v[172:175], v176 offset:59392
	ds_read_b128 v[180:183], v176 offset:60416
	ds_read_b128 v[184:187], v176 offset:61440
	ds_read_b128 v[188:191], v176 offset:62464
	ds_read_b128 v[192:195], v176 offset:63488
	ds_read_b128 v[210:213], v176 offset:64512
	ds_read_b128 v[214:217], v177 offset:7168
	s_add_i32 s3, s5, s45
	v_lshl_add_u64 v[234:235], v[234:235], 0, s[52:53]
	s_mov_b32 m0, s3
	v_lshl_add_u64 v[236:237], v[236:237], 0, s[52:53]
	global_load_lds_dwordx4 v[234:235], off
	s_add_i32 m0, s3, 0x2000
	v_lshl_add_u64 v[238:239], v[238:239], 0, s[52:53]
	global_load_lds_dwordx4 v[236:237], off
	s_mov_b32 m0, s64
	v_lshl_add_u64 v[240:241], v[240:241], 0, s[52:53]
	global_load_lds_dwordx4 v[238:239], off
	s_mov_b32 m0, s65
	v_lshl_add_u64 v[248:249], v[144:145], 0, s[52:53]
	global_load_lds_dwordx4 v[240:241], off
	s_add_i32 s2, s2, s45
	v_lshl_add_u64 v[250:251], v[242:243], 0, s[52:53]
	s_mov_b32 m0, s2
	s_nop 0
	global_load_lds_dwordx4 v[248:249], off
	s_add_i32 m0, s2, 0x2000
	s_nop 0
	global_load_lds_dwordx4 v[250:251], off
	s_waitcnt vmcnt(8) lgkmcnt(0)
	s_barrier
	s_setprio 1
	v_mfma_f32_16x16x32_bf16 v[62:65], v[132:135], v[168:171], v[62:65]
	v_mfma_f32_16x16x32_bf16 v[58:61], v[140:143], v[168:171], v[58:61]
	v_mfma_f32_16x16x32_bf16 v[46:49], v[132:135], v[180:183], v[46:49]
	v_mfma_f32_16x16x32_bf16 v[42:45], v[140:143], v[180:183], v[42:45]
	v_mfma_f32_16x16x32_bf16 v[30:33], v[132:135], v[188:191], v[30:33]
	v_mfma_f32_16x16x32_bf16 v[24:27], v[140:143], v[188:191], v[24:27]
	v_mfma_f32_16x16x32_bf16 v[12:15], v[132:135], v[210:213], v[12:15]
	v_mfma_f32_16x16x32_bf16 v[8:11], v[140:143], v[210:213], v[8:11]
	v_mfma_f32_16x16x32_bf16 v[62:65], v[136:139], v[172:175], v[62:65]
	v_mfma_f32_16x16x32_bf16 v[58:61], v[164:167], v[172:175], v[58:61]
	v_mfma_f32_16x16x32_bf16 v[46:49], v[136:139], v[184:187], v[46:49]
	v_mfma_f32_16x16x32_bf16 v[42:45], v[164:167], v[184:187], v[42:45]
	v_mfma_f32_16x16x32_bf16 v[30:33], v[136:139], v[192:195], v[30:33]
	v_mfma_f32_16x16x32_bf16 v[24:27], v[164:167], v[192:195], v[24:27]
	v_mfma_f32_16x16x32_bf16 v[12:15], v[136:139], v[214:217], v[12:15]
	v_mfma_f32_16x16x32_bf16 v[8:11], v[164:167], v[214:217], v[8:11]
	v_mfma_f32_16x16x32_bf16 v[54:57], v[218:221], v[168:171], v[54:57]
	v_mfma_f32_16x16x32_bf16 v[50:53], v[226:229], v[168:171], v[50:53]
	v_mfma_f32_16x16x32_bf16 v[38:41], v[218:221], v[180:183], v[38:41]
	v_mfma_f32_16x16x32_bf16 v[34:37], v[226:229], v[180:183], v[34:37]
	v_mfma_f32_16x16x32_bf16 v[20:23], v[218:221], v[188:191], v[20:23]
	v_mfma_f32_16x16x32_bf16 v[16:19], v[226:229], v[188:191], v[16:19]
	v_mfma_f32_16x16x32_bf16 v[4:7], v[218:221], v[210:213], v[4:7]
	v_mfma_f32_16x16x32_bf16 v[0:3], v[226:229], v[210:213], v[0:3]
	v_mfma_f32_16x16x32_bf16 v[54:57], v[222:225], v[172:175], v[54:57]
	v_mfma_f32_16x16x32_bf16 v[50:53], v[230:233], v[172:175], v[50:53]
	v_mfma_f32_16x16x32_bf16 v[38:41], v[222:225], v[184:187], v[38:41]
	v_mfma_f32_16x16x32_bf16 v[34:37], v[230:233], v[184:187], v[34:37]
	v_mfma_f32_16x16x32_bf16 v[20:23], v[222:225], v[192:195], v[20:23]
	v_mfma_f32_16x16x32_bf16 v[16:19], v[230:233], v[192:195], v[16:19]
	v_mfma_f32_16x16x32_bf16 v[4:7], v[222:225], v[214:217], v[4:7]
	v_mfma_f32_16x16x32_bf16 v[0:3], v[230:233], v[214:217], v[0:3]
	s_setprio 0
	s_add_u32 s0, s0, 0x100
	s_addc_u32 s1, s1, 0
	v_lshl_add_u64 v[130:131], v[130:131], 0, s[96:97]
	s_cmp_ge_i32 s4, s62
	s_mov_b32 s2, s4
	s_barrier
	s_cbranch_scc0 .LBB0_287
